# v20 + per-unit schedule code: runtime signed division by gsz (always 8) replaced by shift/mask in the 11 in-loop sites
# speedup vs baseline: 1.0063x; 1.0032x over previous
.LBB0_214:
	s_ashr_i32 s20, s26, 31
	s_lshr_b32 s20, s20, 29
	s_add_i32 s20, s26, s20
	s_ashr_i32 s22, s20, 3
	s_and_b32 s20, s20, -8
	s_sub_i32 s20, s26, s20
	s_cmp_lt_i32 s20, 0
	s_cselect_b32 s24, s46, 0x108
	s_mul_i32 s20, s24, s20
	s_add_i32 s20, s20, s22
	s_mul_hi_i32 s22, s20, 0x2e8ba2e9
	s_lshr_b32 s24, s22, 31
	s_ashr_i32 s22, s22, 6
	s_add_i32 s22, s22, s24
	s_lshl_b32 s24, s22, 3
	s_sub_i32 s26, 48, s24
	s_min_i32 s26, s26, 8
	s_mulk_i32 s22, 0x160
	s_sub_i32 s22, s20, s22
	s_mov_b32 s60, s23
	s_mov_b32 s61, s21
	s_ashr_i32 s20, s22, 3
	s_and_b32 s22, s22, 7
	s_add_i32 s24, s22, s24
	s_mov_b32 s22, s25

.LBB0_350:
	s_ashr_i32 s22, s26, 31
	s_lshr_b32 s22, s22, 29
	s_add_i32 s22, s26, s22
	s_ashr_i32 s27, s22, 3
	s_and_b32 s22, s22, -8
	s_sub_i32 s22, s26, s22
	s_cmp_lt_i32 s22, 0
	s_cselect_b32 s26, 49, 48
	s_mul_i32 s22, s26, s22
	s_add_i32 s22, s22, s27
	s_ashr_i32 s26, s22, 31
	s_lshr_b32 s26, s26, 26
	s_add_i32 s26, s22, s26
	s_ashr_i32 s27, s26, 6
	s_lshl_b32 s27, s27, 3
	s_sub_i32 s36, 48, s27
	s_min_i32 s36, s36, 8
	s_andn2_b32 s26, s26, 63
	s_sub_i32 s22, s22, s26
	s_mov_b32 s57, s23
	s_mov_b32 s58, s24
	s_ashr_i32 s55, s22, 3
	s_and_b32 s22, s22, 7
	s_add_i32 s56, s22, s27
	s_mov_b32 s22, s25

.LBB0_1115:
	s_ashr_i32 s16, s22, 31
	s_lshr_b32 s16, s16, 29
	s_add_i32 s16, s22, s16
	s_ashr_i32 s18, s16, 3
	s_and_b32 s16, s16, -8
	s_sub_i32 s16, s22, s16
	s_cmp_lt_i32 s16, 0
	s_cselect_b32 s20, 49, 48
	s_mul_i32 s16, s20, s16
	s_add_i32 s16, s16, s18
	s_ashr_i32 s18, s16, 31
	s_lshr_b32 s18, s18, 26
	s_add_i32 s18, s16, s18
	s_ashr_i32 s20, s18, 6
	s_lshl_b32 s20, s20, 3
	s_sub_i32 s22, 48, s20
	s_min_i32 s22, s22, 8
	s_andn2_b32 s18, s18, 63
	s_sub_i32 s18, s16, s18
	s_mov_b32 s67, s19
	s_mov_b32 s68, s17
	s_ashr_i32 s16, s18, 3
	s_and_b32 s18, s18, 7
	s_add_i32 s18, s18, s20
	s_mov_b32 s20, s21

.LBB0_1308:
	s_ashr_i32 s14, s20, 31
	s_lshr_b32 s14, s14, 29
	s_add_i32 s14, s20, s14
	s_ashr_i32 s16, s14, 3
	s_and_b32 s14, s14, -8
	s_sub_i32 s14, s20, s14
	s_cmp_lt_i32 s14, 0
	s_cselect_b32 s18, s40, 0x108
	s_mul_i32 s14, s18, s14
	s_add_i32 s14, s14, s16
	s_mul_hi_i32 s16, s14, 0x2e8ba2e9
	s_lshr_b32 s18, s16, 31
	s_ashr_i32 s16, s16, 6
	s_add_i32 s16, s16, s18
	s_lshl_b32 s18, s16, 3
	s_sub_i32 s20, 48, s18
	s_min_i32 s20, s20, 8
	s_mulk_i32 s16, 0x160
	s_sub_i32 s16, s14, s16
	s_mov_b32 s66, s17
	s_mov_b32 s67, s15
	s_ashr_i32 s14, s16, 3
	s_and_b32 s16, s16, 7
	s_add_i32 s18, s16, s18
	s_mov_b32 s16, s19

.LBB0_1444:
	s_ashr_i32 s16, s20, 31
	s_lshr_b32 s16, s16, 29
	s_add_i32 s16, s20, s16
	s_ashr_i32 s21, s16, 3
	s_and_b32 s16, s16, -8
	s_sub_i32 s16, s20, s16
	s_cmp_lt_i32 s16, 0
	s_cselect_b32 s20, 49, 48
	s_mul_i32 s16, s20, s16
	s_add_i32 s16, s16, s21
	s_ashr_i32 s20, s16, 31
	s_lshr_b32 s20, s20, 26
	s_add_i32 s20, s16, s20
	s_ashr_i32 s21, s20, 6
	s_lshl_b32 s21, s21, 3
	s_sub_i32 s28, 48, s21
	s_min_i32 s28, s28, 8
	s_andn2_b32 s20, s20, 63
	s_sub_i32 s16, s16, s20
	s_mov_b32 s63, s17
	s_mov_b32 s64, s18
	s_ashr_i32 s61, s16, 3
	s_and_b32 s16, s16, 7
	s_add_i32 s62, s16, s21
	s_mov_b32 s16, s19

.LBB0_1966:
	s_ashr_i32 s18, s24, 31
	s_lshr_b32 s18, s18, 29
	s_add_i32 s18, s24, s18
	s_ashr_i32 s20, s18, 3
	s_and_b32 s18, s18, -8
	s_sub_i32 s18, s24, s18
	s_cmp_lt_i32 s18, 0
	s_cselect_b32 s22, s40, 0x48
	s_mul_i32 s18, s22, s18
	s_add_i32 s18, s18, s20
	s_mul_hi_i32 s20, s18, 0x2aaaaaab
	s_lshr_b32 s22, s20, 31
	s_ashr_i32 s20, s20, 4
	s_add_i32 s20, s20, s22
	s_lshl_b32 s22, s20, 3
	s_sub_i32 s24, 48, s22
	s_min_i32 s24, s24, 8
	s_mulk_i32 s20, 0x60
	s_sub_i32 s20, s18, s20
	s_mov_b32 s66, s21
	s_mov_b32 s67, s19
	s_ashr_i32 s18, s20, 3
	s_and_b32 s20, s20, 7
	s_add_i32 s22, s20, s22
	s_mov_b32 s20, s23

.LBB0_2540:
	s_ashr_i32 s14, s20, 31
	s_lshr_b32 s14, s14, 29
	s_add_i32 s14, s20, s14
	s_ashr_i32 s16, s14, 3
	s_and_b32 s14, s14, -8
	s_sub_i32 s14, s20, s14
	s_cmp_lt_i32 s14, 0
	s_cselect_b32 s18, s40, 0x108
	s_mul_i32 s14, s18, s14
	s_add_i32 s14, s14, s16
	s_mul_hi_i32 s16, s14, 0x2e8ba2e9
	s_lshr_b32 s18, s16, 31
	s_ashr_i32 s16, s16, 6
	s_add_i32 s16, s16, s18
	s_lshl_b32 s18, s16, 3
	s_sub_i32 s20, 48, s18
	s_min_i32 s20, s20, 8
	s_mulk_i32 s16, 0x160
	s_sub_i32 s16, s14, s16
	s_mov_b32 s66, s15
	s_mov_b32 s67, s17
	s_ashr_i32 s14, s16, 3
	s_and_b32 s16, s16, 7
	s_add_i32 s18, s16, s18
	s_mov_b32 s16, s19
